# speedup vs baseline: 1.0863x; 1.0127x over previous
; template <int NS, bool LORA, int mat> ...
;     ...
;   const int ch = 64 * head + lane;
;   const float kk_c = p.k_k[ch], ka_c = p.k_a[ch], rk_c = p.r_k[ch];
;   const float mu_r = p.mu_shift[ch], mu_k = p.mu_shift[1024 + ch], mu_v = p.mu_shift[2048 + ch];
;   uint4 la[2][6];
;   u16 rv[2][NS][9];
.LBB0_1118:
	s_lshl_b32 s4, s89, 7
	s_add_i32 s4, s4, s60
	s_lshr_b32 s10, s4, 5
	s_lshl_b64 s[4:5], s[10:11], 11
	s_waitcnt vmcnt(17)
	v_mov_b32 v144, v146
	s_add_u32 s90, s4, 0x4000
	v_ashrrev_i32_e32 v7, 6, v144
	s_waitcnt vmcnt(13)
	v_and_b32_e32 v149, 63, v144
	v_cmp_lt_i32_e32 vcc, 3, v7
	s_and_saveexec_b64 s[4:5], vcc
	s_xor_b64 s[52:53], exec, s[4:5]
	s_cbranch_execz .LBB0_1213
	v_cmp_lt_i32_e32 vcc, 4, v7
	s_and_saveexec_b64 s[4:5], vcc
	s_xor_b64 s[54:55], exec, s[4:5]
	s_cbranch_execz .LBB0_1188
	v_cmp_ne_u32_e32 vcc, 5, v7
	s_and_saveexec_b64 s[4:5], vcc
	s_xor_b64 s[6:7], exec, s[4:5]
	s_cbranch_execz .LBB0_1155
	v_readfirstlane_b32 s4, v7
	v_and_b32_e32 v48, 7, v149
	v_lshrrev_b32_e32 v49, 3, v149
	s_sub_i32 s4, s4, 6
	s_lshl_b32 s4, s4, 3
	v_add_u32_e32 v50, s4, v49
	v_lshl_add_u32 v51, v48, 3, s62
	s_mul_i32 s4, s90, 0x1c00
	v_lshlrev_b32_e32 v52, 1, v51
	v_add_u32_e32 v52, 0x800, v52
	v_add_u32_e32 v52, s4, v52
	v_lshlrev_b32_e32 v51, 2, v51
	v_mov_b32_e32 v53, 0x1c00
	v_mov_b32_e32 v58, 0x7ff
	v_mov_b32_e32 v59, -16
	v_cndmask_b32_e64 v59, v59, 16, s[0:1]
	v_add_u32_e32 v205, 0x1000, v51
	v_add_u32_e32 v206, 0x2000, v51
	global_load_dwordx4 v[0:3], v51, s[50:51]
	global_load_dwordx4 v[4:7], v51, s[50:51] offset:16
	global_load_dwordx4 v[8:11], v51, s[16:17]
	global_load_dwordx4 v[12:15], v51, s[16:17] offset:16
	global_load_dwordx4 v[16:19], v51, s[18:19]
	global_load_dwordx4 v[20:23], v51, s[18:19] offset:16
	global_load_dwordx4 v[24:27], v51, s[38:39]
	global_load_dwordx4 v[28:31], v51, s[38:39] offset:16
	global_load_dwordx4 v[32:35], v205, s[38:39]
	global_load_dwordx4 v[36:39], v205, s[38:39] offset:16
	global_load_dwordx4 v[40:43], v206, s[38:39]
	global_load_dwordx4 v[44:47], v206, s[38:39] offset:16
	v_mul_u32_u24_e32 v54, 0x500, v50
	v_lshlrev_b32_e32 v55, 8, v50
	v_lshl_add_u32 v54, v48, 5, v54
	v_lshl_add_u32 v55, v48, 5, v55
	v_add_u32_e32 v54, 0x5000, v54
	v_add_u32_e32 v55, 0x3000, v55
	v_sub_u32_e32 v205, v58, v50
	v_cndmask_b32_e64 v56, v205, v50, s[0:1]
	v_cmp_eq_u32_e64 s[8:9], 0, v48
	s_waitcnt vmcnt(0)
	v_cmp_lt_i32_e64 s[4:5], 0, v56
	v_cmp_gt_i32_e64 s[58:59], v58, v56
	v_mad_u32_u24 v205, v56, v53, v52
	s_nop 0
	v_cndmask_b32_e64 v206, 0, v53, s[4:5]
	v_cndmask_b32_e64 v207, 0, v53, s[58:59]
	v_cndmask_b32_e64 v60, 0, 1.0, s[4:5]
	v_cndmask_b32_e64 v61, 0, 1.0, s[58:59]
	v_sub_u32_e32 v206, v205, v206
	v_add_u32_e32 v207, v205, v207
	global_load_dwordx4 v[64:67], v205, s[72:73] offset:-2048
	global_load_dwordx4 v[68:71], v205, s[72:73]
	global_load_dwordx4 v[72:75], v205, s[72:73] offset:2048
	global_load_dwordx4 v[76:79], v206, s[72:73] offset:-2048
	global_load_dwordx4 v[80:83], v206, s[72:73]
	global_load_dwordx4 v[84:87], v206, s[72:73] offset:2048
	global_load_dwordx4 v[88:91], v207, s[72:73] offset:-2048
	global_load_dwordx4 v[92:95], v207, s[72:73]
	global_load_dwordx4 v[96:99], v207, s[72:73] offset:2048
	s_mov_b32 s10, 1
	s_waitcnt lgkmcnt(0)
	s_barrier
.Lmy_ks_loop:
	v_add_u32_e32 v57, v59, v56
	v_cmp_lt_i32_e64 s[4:5], 0, v57
	v_cmp_gt_i32_e64 s[58:59], v58, v57
	v_mad_u32_u24 v205, v57, v53, v52
	s_nop 0
	v_cndmask_b32_e64 v206, 0, v53, s[4:5]
	v_cndmask_b32_e64 v207, 0, v53, s[58:59]
	v_cndmask_b32_e64 v62, 0, 1.0, s[4:5]
	v_cndmask_b32_e64 v63, 0, 1.0, s[58:59]
	v_sub_u32_e32 v206, v205, v206
	v_add_u32_e32 v207, v205, v207
	global_load_dwordx4 v[100:103], v205, s[72:73] offset:-2048
	global_load_dwordx4 v[104:107], v205, s[72:73]
	global_load_dwordx4 v[108:111], v205, s[72:73] offset:2048
	global_load_dwordx4 v[112:115], v206, s[72:73] offset:-2048
	global_load_dwordx4 v[116:119], v206, s[72:73]
	global_load_dwordx4 v[120:123], v206, s[72:73] offset:2048
	global_load_dwordx4 v[124:127], v207, s[72:73] offset:-2048
	global_load_dwordx4 v[128:131], v207, s[72:73]
	global_load_dwordx4 v[132:135], v207, s[72:73] offset:2048
	ds_read_b128 v[184:187], v55 offset:0
	ds_read_b128 v[188:191], v55 offset:16
	s_waitcnt vmcnt(9)
	v_lshlrev_b32_e32 v136, 16, v64
	v_lshlrev_b32_e32 v192, 16, v76
	v_lshlrev_b32_e32 v193, 16, v88
	v_mul_f32_e32 v193, v61, v193
	v_fmac_f32_e32 v193, v60, v192
	v_fma_f32 v192, v193, 0.5, -v136
	v_fmac_f32_e32 v136, v24, v192
	v_and_b32_e32 v137, 0xffff0000, v64
	v_and_b32_e32 v192, 0xffff0000, v76
	v_and_b32_e32 v193, 0xffff0000, v88
	v_mul_f32_e32 v193, v61, v193
	v_fmac_f32_e32 v193, v60, v192
	v_fma_f32 v192, v193, 0.5, -v137
	v_fmac_f32_e32 v137, v25, v192
	v_lshlrev_b32_e32 v138, 16, v65
	v_lshlrev_b32_e32 v192, 16, v77
	v_lshlrev_b32_e32 v193, 16, v89
	v_mul_f32_e32 v193, v61, v193
	v_fmac_f32_e32 v193, v60, v192
	v_fma_f32 v192, v193, 0.5, -v138
	v_fmac_f32_e32 v138, v26, v192
	v_and_b32_e32 v139, 0xffff0000, v65
	v_and_b32_e32 v192, 0xffff0000, v77
	v_and_b32_e32 v193, 0xffff0000, v89
	v_mul_f32_e32 v193, v61, v193
	v_fmac_f32_e32 v193, v60, v192
	v_fma_f32 v192, v193, 0.5, -v139
	v_fmac_f32_e32 v139, v27, v192
	v_lshlrev_b32_e32 v140, 16, v66
	v_lshlrev_b32_e32 v192, 16, v78
	v_lshlrev_b32_e32 v193, 16, v90
	v_mul_f32_e32 v193, v61, v193
	v_fmac_f32_e32 v193, v60, v192
	v_fma_f32 v192, v193, 0.5, -v140
	v_fmac_f32_e32 v140, v28, v192
	v_and_b32_e32 v141, 0xffff0000, v66
	v_and_b32_e32 v192, 0xffff0000, v78
	v_and_b32_e32 v193, 0xffff0000, v90
	v_mul_f32_e32 v193, v61, v193
	v_fmac_f32_e32 v193, v60, v192
	v_fma_f32 v192, v193, 0.5, -v141
	v_fmac_f32_e32 v141, v29, v192
	v_lshlrev_b32_e32 v142, 16, v67
	v_lshlrev_b32_e32 v192, 16, v79
	v_lshlrev_b32_e32 v193, 16, v91
	v_mul_f32_e32 v193, v61, v193
	v_fmac_f32_e32 v193, v60, v192
	v_fma_f32 v192, v193, 0.5, -v142
	v_fmac_f32_e32 v142, v30, v192
	v_and_b32_e32 v143, 0xffff0000, v67
	v_and_b32_e32 v192, 0xffff0000, v79
	v_and_b32_e32 v193, 0xffff0000, v91
	v_mul_f32_e32 v193, v61, v193
	v_fmac_f32_e32 v193, v60, v192
	v_fma_f32 v192, v193, 0.5, -v143
	v_fmac_f32_e32 v143, v31, v192
	v_lshlrev_b32_e32 v208, 16, v68
	v_lshlrev_b32_e32 v192, 16, v80
	v_lshlrev_b32_e32 v193, 16, v92
	v_mul_f32_e32 v193, v61, v193
	v_fmac_f32_e32 v193, v60, v192
	v_fma_f32 v192, v193, 0.5, -v208
	v_fmac_f32_e32 v208, v32, v192
	v_and_b32_e32 v209, 0xffff0000, v68
	v_and_b32_e32 v192, 0xffff0000, v80
	v_and_b32_e32 v193, 0xffff0000, v92
	v_mul_f32_e32 v193, v61, v193
	v_fmac_f32_e32 v193, v60, v192
	v_fma_f32 v192, v193, 0.5, -v209
	v_fmac_f32_e32 v209, v33, v192
	v_lshlrev_b32_e32 v210, 16, v69
	v_lshlrev_b32_e32 v192, 16, v81
	v_lshlrev_b32_e32 v193, 16, v93
	v_mul_f32_e32 v193, v61, v193
	v_fmac_f32_e32 v193, v60, v192
	v_fma_f32 v192, v193, 0.5, -v210
	v_fmac_f32_e32 v210, v34, v192
	v_and_b32_e32 v211, 0xffff0000, v69
	v_and_b32_e32 v192, 0xffff0000, v81
	v_and_b32_e32 v193, 0xffff0000, v93
	v_mul_f32_e32 v193, v61, v193
	v_fmac_f32_e32 v193, v60, v192
	v_fma_f32 v192, v193, 0.5, -v211
	v_fmac_f32_e32 v211, v35, v192
	v_lshlrev_b32_e32 v212, 16, v70
	v_lshlrev_b32_e32 v192, 16, v82
	v_lshlrev_b32_e32 v193, 16, v94
	v_mul_f32_e32 v193, v61, v193
	v_fmac_f32_e32 v193, v60, v192
	v_fma_f32 v192, v193, 0.5, -v212
	v_fmac_f32_e32 v212, v36, v192
	v_and_b32_e32 v213, 0xffff0000, v70
	v_and_b32_e32 v192, 0xffff0000, v82
	v_and_b32_e32 v193, 0xffff0000, v94
	v_mul_f32_e32 v193, v61, v193
	v_fmac_f32_e32 v193, v60, v192
	v_fma_f32 v192, v193, 0.5, -v213
	v_fmac_f32_e32 v213, v37, v192
	v_lshlrev_b32_e32 v214, 16, v71
	v_lshlrev_b32_e32 v192, 16, v83
	v_lshlrev_b32_e32 v193, 16, v95
	v_mul_f32_e32 v193, v61, v193
	v_fmac_f32_e32 v193, v60, v192
	v_fma_f32 v192, v193, 0.5, -v214
	v_fmac_f32_e32 v214, v38, v192
	v_and_b32_e32 v215, 0xffff0000, v71
	v_and_b32_e32 v192, 0xffff0000, v83
	v_and_b32_e32 v193, 0xffff0000, v95
	v_mul_f32_e32 v193, v61, v193
	v_fmac_f32_e32 v193, v60, v192
	v_fma_f32 v192, v193, 0.5, -v215
	v_fmac_f32_e32 v215, v39, v192
	v_lshlrev_b32_e32 v152, 16, v72
	v_lshlrev_b32_e32 v192, 16, v84
	v_lshlrev_b32_e32 v193, 16, v96
	v_mul_f32_e32 v193, v61, v193
	v_fmac_f32_e32 v193, v60, v192
	v_fma_f32 v192, v193, 0.5, -v152
	v_fmac_f32_e32 v152, v40, v192
	v_and_b32_e32 v153, 0xffff0000, v72
	v_and_b32_e32 v192, 0xffff0000, v84
	v_and_b32_e32 v193, 0xffff0000, v96
	v_mul_f32_e32 v193, v61, v193
	v_fmac_f32_e32 v193, v60, v192
	v_fma_f32 v192, v193, 0.5, -v153
	v_fmac_f32_e32 v153, v41, v192
	v_lshlrev_b32_e32 v154, 16, v73
	v_lshlrev_b32_e32 v192, 16, v85
	v_lshlrev_b32_e32 v193, 16, v97
	v_mul_f32_e32 v193, v61, v193
	v_fmac_f32_e32 v193, v60, v192
	v_fma_f32 v192, v193, 0.5, -v154
	v_fmac_f32_e32 v154, v42, v192
	v_and_b32_e32 v155, 0xffff0000, v73
	v_and_b32_e32 v192, 0xffff0000, v85
	v_and_b32_e32 v193, 0xffff0000, v97
	v_mul_f32_e32 v193, v61, v193
	v_fmac_f32_e32 v193, v60, v192
	v_fma_f32 v192, v193, 0.5, -v155
	v_fmac_f32_e32 v155, v43, v192
	v_lshlrev_b32_e32 v156, 16, v74
	v_lshlrev_b32_e32 v192, 16, v86
	v_lshlrev_b32_e32 v193, 16, v98
	v_mul_f32_e32 v193, v61, v193
	v_fmac_f32_e32 v193, v60, v192
	v_fma_f32 v192, v193, 0.5, -v156
	v_fmac_f32_e32 v156, v44, v192
	v_and_b32_e32 v157, 0xffff0000, v74
	v_and_b32_e32 v192, 0xffff0000, v86
	v_and_b32_e32 v193, 0xffff0000, v98
	v_mul_f32_e32 v193, v61, v193
	v_fmac_f32_e32 v193, v60, v192
	v_fma_f32 v192, v193, 0.5, -v157
	v_fmac_f32_e32 v157, v45, v192
	v_lshlrev_b32_e32 v158, 16, v75
	v_lshlrev_b32_e32 v192, 16, v87
	v_lshlrev_b32_e32 v193, 16, v99
	v_mul_f32_e32 v193, v61, v193
	v_fmac_f32_e32 v193, v60, v192
	v_fma_f32 v192, v193, 0.5, -v158
	v_fmac_f32_e32 v158, v46, v192
	v_and_b32_e32 v159, 0xffff0000, v75
	v_and_b32_e32 v192, 0xffff0000, v87
	v_and_b32_e32 v193, 0xffff0000, v99
	v_mul_f32_e32 v193, v61, v193
	v_fmac_f32_e32 v193, v60, v192
	v_fma_f32 v192, v193, 0.5, -v159
	v_fmac_f32_e32 v159, v47, v192
	v_mul_f32_e32 v160, v0, v208
	v_mul_f32_e32 v161, v1, v209
	v_mul_f32_e32 v162, v2, v210
	v_mul_f32_e32 v163, v3, v211
	v_mul_f32_e32 v164, v4, v212
	v_mul_f32_e32 v165, v5, v213
	v_mul_f32_e32 v166, v6, v214
	v_mul_f32_e32 v167, v7, v215
	v_mul_f32_e32 v200, v160, v160
	v_fmac_f32_e32 v200, v161, v161
	v_fmac_f32_e32 v200, v162, v162
	v_fmac_f32_e32 v200, v163, v163
	v_fmac_f32_e32 v200, v164, v164
	v_fmac_f32_e32 v200, v165, v165
	v_fmac_f32_e32 v200, v166, v166
	v_fmac_f32_e32 v200, v167, v167
	s_waitcnt lgkmcnt(0)
	v_add_f32_e32 v192, -1.0, v184
	v_fma_f32 v192, v8, v192, 1.0
	v_mul_f32_e32 v176, v208, v192
	v_add_f32_dpp v200, v200, v200 quad_perm:[1,0,3,2] row_mask:0xf bank_mask:0xf bound_ctrl:1
	v_add_f32_e32 v192, -1.0, v185
	v_fma_f32 v192, v9, v192, 1.0
	v_mul_f32_e32 v177, v209, v192
	v_add_f32_dpp v200, v200, v200 quad_perm:[2,3,0,1] row_mask:0xf bank_mask:0xf bound_ctrl:1
	v_add_f32_e32 v192, -1.0, v186
	v_fma_f32 v192, v10, v192, 1.0
	v_mul_f32_e32 v178, v210, v192
	v_add_f32_dpp v200, v200, v200 row_half_mirror row_mask:0xf bank_mask:0xf bound_ctrl:1
	v_add_f32_e32 v192, -1.0, v187
	v_fma_f32 v192, v11, v192, 1.0
	v_mul_f32_e32 v179, v211, v192
	v_add_f32_e32 v192, -1.0, v188
	v_fma_f32 v192, v12, v192, 1.0
	v_mul_f32_e32 v180, v212, v192
	v_add_f32_e32 v192, -1.0, v189
	v_fma_f32 v192, v13, v192, 1.0
	v_mul_f32_e32 v181, v213, v192
	v_add_f32_e32 v192, -1.0, v190
	v_fma_f32 v192, v14, v192, 1.0
	v_mul_f32_e32 v182, v214, v192
	v_add_f32_e32 v192, -1.0, v191
	v_fma_f32 v192, v15, v192, 1.0
	v_mul_f32_e32 v183, v215, v192
	v_max_f32_e32 v200, v200, v200
	v_max_f32_e32 v200, 0x179abe15, v200
	v_rsq_f32_e32 v201, v200
	v_mul_f32_e32 v192, v136, v176
	v_mul_f32_e32 v202, v16, v192
	v_mul_f32_e32 v160, v160, v201
	v_mul_f32_e32 v161, v161, v201
	v_mul_f32_e32 v162, v162, v201
	v_mul_f32_e32 v163, v163, v201
	v_mul_f32_e32 v164, v164, v201
	v_mul_f32_e32 v165, v165, v201
	v_mul_f32_e32 v166, v166, v201
	v_mul_f32_e32 v167, v167, v201
	v_mul_f32_e32 v168, v184, v160
	v_mul_f32_e32 v169, v185, v161
	v_mul_f32_e32 v170, v186, v162
	v_mul_f32_e32 v171, v187, v163
	v_mul_f32_e32 v172, v188, v164
	v_mul_f32_e32 v173, v189, v165
	v_mul_f32_e32 v174, v190, v166
	v_mul_f32_e32 v175, v191, v167
	ds_write_b128 v54, v[160:163] offset:0
	ds_write_b128 v54, v[164:167] offset:16
	ds_write_b128 v54, v[168:171] offset:256
	ds_write_b128 v54, v[172:175] offset:272
	ds_write_b128 v54, v[176:179] offset:512
	ds_write_b128 v54, v[180:183] offset:528
	ds_write_b128 v54, v[136:139] offset:768
	ds_write_b128 v54, v[140:143] offset:784
	ds_write_b128 v54, v[152:155] offset:1024
	ds_write_b128 v54, v[156:159] offset:1040
	v_mul_f32_e32 v192, v137, v177
	v_fmac_f32_e32 v202, v17, v192
	v_mul_f32_e32 v192, v138, v178
	v_fmac_f32_e32 v202, v18, v192
	v_mul_f32_e32 v192, v139, v179
	v_fmac_f32_e32 v202, v19, v192
	v_mul_f32_e32 v192, v140, v180
	v_fmac_f32_e32 v202, v20, v192
	v_mul_f32_e32 v192, v141, v181
	v_fmac_f32_e32 v202, v21, v192
	v_mul_f32_e32 v192, v142, v182
	v_fmac_f32_e32 v202, v22, v192
	v_mul_f32_e32 v192, v143, v183
	v_fmac_f32_e32 v202, v23, v192
	s_nop 1
	v_add_f32_dpp v202, v202, v202 quad_perm:[1,0,3,2] row_mask:0xf bank_mask:0xf bound_ctrl:1
	s_nop 1
	v_add_f32_dpp v202, v202, v202 quad_perm:[2,3,0,1] row_mask:0xf bank_mask:0xf bound_ctrl:1
	s_nop 1
	v_add_f32_dpp v202, v202, v202 row_half_mirror row_mask:0xf bank_mask:0xf bound_ctrl:1
	v_add_u32_e32 v205, s90, v56
	v_lshl_add_u32 v205, v205, 7, s64
	s_and_saveexec_b64 s[56:57], s[8:9]
	global_store_dword v205, v202, s[24:25]
	s_or_b64 exec, exec, s[56:57]
	v_mov_b32_e32 v56, v57
	s_waitcnt lgkmcnt(0)
	s_barrier
	s_add_i32 s10, s10, 1
	v_add_u32_e32 v57, v59, v56
	s_cmp_lt_u32 s10, 128
	s_cbranch_scc0 .Lmy_ksb_nonext
	v_cmp_lt_i32_e64 s[4:5], 0, v57
	v_cmp_gt_i32_e64 s[58:59], v58, v57
	v_mad_u32_u24 v205, v57, v53, v52
	s_nop 0
	v_cndmask_b32_e64 v206, 0, v53, s[4:5]
	v_cndmask_b32_e64 v207, 0, v53, s[58:59]
	v_cndmask_b32_e64 v60, 0, 1.0, s[4:5]
	v_cndmask_b32_e64 v61, 0, 1.0, s[58:59]
	v_sub_u32_e32 v206, v205, v206
	v_add_u32_e32 v207, v205, v207
	global_load_dwordx4 v[64:67], v205, s[72:73] offset:-2048
	global_load_dwordx4 v[68:71], v205, s[72:73]
	global_load_dwordx4 v[72:75], v205, s[72:73] offset:2048
	global_load_dwordx4 v[76:79], v206, s[72:73] offset:-2048
	global_load_dwordx4 v[80:83], v206, s[72:73]
	global_load_dwordx4 v[84:87], v206, s[72:73] offset:2048
	global_load_dwordx4 v[88:91], v207, s[72:73] offset:-2048
	global_load_dwordx4 v[92:95], v207, s[72:73]
	global_load_dwordx4 v[96:99], v207, s[72:73] offset:2048
	ds_read_b128 v[184:187], v55 offset:4096
	ds_read_b128 v[188:191], v55 offset:4112
	s_waitcnt vmcnt(9)
	s_branch .Lmy_ksb_go

.Lmy_ksb_go:
	v_lshlrev_b32_e32 v136, 16, v100
	v_lshlrev_b32_e32 v192, 16, v112
	v_lshlrev_b32_e32 v193, 16, v124
	v_mul_f32_e32 v193, v63, v193
	v_fmac_f32_e32 v193, v62, v192
	v_fma_f32 v192, v193, 0.5, -v136
	v_fmac_f32_e32 v136, v24, v192
	v_and_b32_e32 v137, 0xffff0000, v100
	v_and_b32_e32 v192, 0xffff0000, v112
	v_and_b32_e32 v193, 0xffff0000, v124
	v_mul_f32_e32 v193, v63, v193
	v_fmac_f32_e32 v193, v62, v192
	v_fma_f32 v192, v193, 0.5, -v137
	v_fmac_f32_e32 v137, v25, v192
	v_lshlrev_b32_e32 v138, 16, v101
	v_lshlrev_b32_e32 v192, 16, v113
	v_lshlrev_b32_e32 v193, 16, v125
	v_mul_f32_e32 v193, v63, v193
	v_fmac_f32_e32 v193, v62, v192
	v_fma_f32 v192, v193, 0.5, -v138
	v_fmac_f32_e32 v138, v26, v192
	v_and_b32_e32 v139, 0xffff0000, v101
	v_and_b32_e32 v192, 0xffff0000, v113
	v_and_b32_e32 v193, 0xffff0000, v125
	v_mul_f32_e32 v193, v63, v193
	v_fmac_f32_e32 v193, v62, v192
	v_fma_f32 v192, v193, 0.5, -v139
	v_fmac_f32_e32 v139, v27, v192
	v_lshlrev_b32_e32 v140, 16, v102
	v_lshlrev_b32_e32 v192, 16, v114
	v_lshlrev_b32_e32 v193, 16, v126
	v_mul_f32_e32 v193, v63, v193
	v_fmac_f32_e32 v193, v62, v192
	v_fma_f32 v192, v193, 0.5, -v140
	v_fmac_f32_e32 v140, v28, v192
	v_and_b32_e32 v141, 0xffff0000, v102
	v_and_b32_e32 v192, 0xffff0000, v114
	v_and_b32_e32 v193, 0xffff0000, v126
	v_mul_f32_e32 v193, v63, v193
	v_fmac_f32_e32 v193, v62, v192
	v_fma_f32 v192, v193, 0.5, -v141
	v_fmac_f32_e32 v141, v29, v192
	v_lshlrev_b32_e32 v142, 16, v103
	v_lshlrev_b32_e32 v192, 16, v115
	v_lshlrev_b32_e32 v193, 16, v127
	v_mul_f32_e32 v193, v63, v193
	v_fmac_f32_e32 v193, v62, v192
	v_fma_f32 v192, v193, 0.5, -v142
	v_fmac_f32_e32 v142, v30, v192
	v_and_b32_e32 v143, 0xffff0000, v103
	v_and_b32_e32 v192, 0xffff0000, v115
	v_and_b32_e32 v193, 0xffff0000, v127
	v_mul_f32_e32 v193, v63, v193
	v_fmac_f32_e32 v193, v62, v192
	v_fma_f32 v192, v193, 0.5, -v143
	v_fmac_f32_e32 v143, v31, v192
	v_lshlrev_b32_e32 v208, 16, v104
	v_lshlrev_b32_e32 v192, 16, v116
	v_lshlrev_b32_e32 v193, 16, v128
	v_mul_f32_e32 v193, v63, v193
	v_fmac_f32_e32 v193, v62, v192
	v_fma_f32 v192, v193, 0.5, -v208
	v_fmac_f32_e32 v208, v32, v192
	v_and_b32_e32 v209, 0xffff0000, v104
	v_and_b32_e32 v192, 0xffff0000, v116
	v_and_b32_e32 v193, 0xffff0000, v128
	v_mul_f32_e32 v193, v63, v193
	v_fmac_f32_e32 v193, v62, v192
	v_fma_f32 v192, v193, 0.5, -v209
	v_fmac_f32_e32 v209, v33, v192
	v_lshlrev_b32_e32 v210, 16, v105
	v_lshlrev_b32_e32 v192, 16, v117
	v_lshlrev_b32_e32 v193, 16, v129
	v_mul_f32_e32 v193, v63, v193
	v_fmac_f32_e32 v193, v62, v192
	v_fma_f32 v192, v193, 0.5, -v210
	v_fmac_f32_e32 v210, v34, v192
	v_and_b32_e32 v211, 0xffff0000, v105
	v_and_b32_e32 v192, 0xffff0000, v117
	v_and_b32_e32 v193, 0xffff0000, v129
	v_mul_f32_e32 v193, v63, v193
	v_fmac_f32_e32 v193, v62, v192
	v_fma_f32 v192, v193, 0.5, -v211
	v_fmac_f32_e32 v211, v35, v192
	v_lshlrev_b32_e32 v212, 16, v106
	v_lshlrev_b32_e32 v192, 16, v118
	v_lshlrev_b32_e32 v193, 16, v130
	v_mul_f32_e32 v193, v63, v193
	v_fmac_f32_e32 v193, v62, v192
	v_fma_f32 v192, v193, 0.5, -v212
	v_fmac_f32_e32 v212, v36, v192
	v_and_b32_e32 v213, 0xffff0000, v106
	v_and_b32_e32 v192, 0xffff0000, v118
	v_and_b32_e32 v193, 0xffff0000, v130
	v_mul_f32_e32 v193, v63, v193
	v_fmac_f32_e32 v193, v62, v192
	v_fma_f32 v192, v193, 0.5, -v213
	v_fmac_f32_e32 v213, v37, v192
	v_lshlrev_b32_e32 v214, 16, v107
	v_lshlrev_b32_e32 v192, 16, v119
	v_lshlrev_b32_e32 v193, 16, v131
	v_mul_f32_e32 v193, v63, v193
	v_fmac_f32_e32 v193, v62, v192
	v_fma_f32 v192, v193, 0.5, -v214
	v_fmac_f32_e32 v214, v38, v192
	v_and_b32_e32 v215, 0xffff0000, v107
	v_and_b32_e32 v192, 0xffff0000, v119
	v_and_b32_e32 v193, 0xffff0000, v131
	v_mul_f32_e32 v193, v63, v193
	v_fmac_f32_e32 v193, v62, v192
	v_fma_f32 v192, v193, 0.5, -v215
	v_fmac_f32_e32 v215, v39, v192
	v_lshlrev_b32_e32 v152, 16, v108
	v_lshlrev_b32_e32 v192, 16, v120
	v_lshlrev_b32_e32 v193, 16, v132
	v_mul_f32_e32 v193, v63, v193
	v_fmac_f32_e32 v193, v62, v192
	v_fma_f32 v192, v193, 0.5, -v152
	v_fmac_f32_e32 v152, v40, v192
	v_and_b32_e32 v153, 0xffff0000, v108
	v_and_b32_e32 v192, 0xffff0000, v120
	v_and_b32_e32 v193, 0xffff0000, v132
	v_mul_f32_e32 v193, v63, v193
	v_fmac_f32_e32 v193, v62, v192
	v_fma_f32 v192, v193, 0.5, -v153
	v_fmac_f32_e32 v153, v41, v192
	v_lshlrev_b32_e32 v154, 16, v109
	v_lshlrev_b32_e32 v192, 16, v121
	v_lshlrev_b32_e32 v193, 16, v133
	v_mul_f32_e32 v193, v63, v193
	v_fmac_f32_e32 v193, v62, v192
	v_fma_f32 v192, v193, 0.5, -v154
	v_fmac_f32_e32 v154, v42, v192
	v_and_b32_e32 v155, 0xffff0000, v109
	v_and_b32_e32 v192, 0xffff0000, v121
	v_and_b32_e32 v193, 0xffff0000, v133
	v_mul_f32_e32 v193, v63, v193
	v_fmac_f32_e32 v193, v62, v192
	v_fma_f32 v192, v193, 0.5, -v155
	v_fmac_f32_e32 v155, v43, v192
	v_lshlrev_b32_e32 v156, 16, v110
	v_lshlrev_b32_e32 v192, 16, v122
	v_lshlrev_b32_e32 v193, 16, v134
	v_mul_f32_e32 v193, v63, v193
	v_fmac_f32_e32 v193, v62, v192
	v_fma_f32 v192, v193, 0.5, -v156
	v_fmac_f32_e32 v156, v44, v192
	v_and_b32_e32 v157, 0xffff0000, v110
	v_and_b32_e32 v192, 0xffff0000, v122
	v_and_b32_e32 v193, 0xffff0000, v134
	v_mul_f32_e32 v193, v63, v193
	v_fmac_f32_e32 v193, v62, v192
	v_fma_f32 v192, v193, 0.5, -v157
	v_fmac_f32_e32 v157, v45, v192
	v_lshlrev_b32_e32 v158, 16, v111
	v_lshlrev_b32_e32 v192, 16, v123
	v_lshlrev_b32_e32 v193, 16, v135
	v_mul_f32_e32 v193, v63, v193
	v_fmac_f32_e32 v193, v62, v192
	v_fma_f32 v192, v193, 0.5, -v158
	v_fmac_f32_e32 v158, v46, v192
	v_and_b32_e32 v159, 0xffff0000, v111
	v_and_b32_e32 v192, 0xffff0000, v123
	v_and_b32_e32 v193, 0xffff0000, v135
	v_mul_f32_e32 v193, v63, v193
	v_fmac_f32_e32 v193, v62, v192
	v_fma_f32 v192, v193, 0.5, -v159
	v_fmac_f32_e32 v159, v47, v192
	v_mul_f32_e32 v160, v0, v208
	v_mul_f32_e32 v161, v1, v209
	v_mul_f32_e32 v162, v2, v210
	v_mul_f32_e32 v163, v3, v211
	v_mul_f32_e32 v164, v4, v212
	v_mul_f32_e32 v165, v5, v213
	v_mul_f32_e32 v166, v6, v214
	v_mul_f32_e32 v167, v7, v215
	v_mul_f32_e32 v200, v160, v160
	v_fmac_f32_e32 v200, v161, v161
	v_fmac_f32_e32 v200, v162, v162
	v_fmac_f32_e32 v200, v163, v163
	v_fmac_f32_e32 v200, v164, v164
	v_fmac_f32_e32 v200, v165, v165
	v_fmac_f32_e32 v200, v166, v166
	v_fmac_f32_e32 v200, v167, v167
	s_waitcnt lgkmcnt(0)
	v_add_f32_e32 v192, -1.0, v184
	v_fma_f32 v192, v8, v192, 1.0
	v_mul_f32_e32 v176, v208, v192
	v_add_f32_dpp v200, v200, v200 quad_perm:[1,0,3,2] row_mask:0xf bank_mask:0xf bound_ctrl:1
	v_add_f32_e32 v192, -1.0, v185
	v_fma_f32 v192, v9, v192, 1.0
	v_mul_f32_e32 v177, v209, v192
	v_add_f32_dpp v200, v200, v200 quad_perm:[2,3,0,1] row_mask:0xf bank_mask:0xf bound_ctrl:1
	v_add_f32_e32 v192, -1.0, v186
	v_fma_f32 v192, v10, v192, 1.0
	v_mul_f32_e32 v178, v210, v192
	v_add_f32_dpp v200, v200, v200 row_half_mirror row_mask:0xf bank_mask:0xf bound_ctrl:1
	v_add_f32_e32 v192, -1.0, v187
	v_fma_f32 v192, v11, v192, 1.0
	v_mul_f32_e32 v179, v211, v192
	v_add_f32_e32 v192, -1.0, v188
	v_fma_f32 v192, v12, v192, 1.0
	v_mul_f32_e32 v180, v212, v192
	v_add_f32_e32 v192, -1.0, v189
	v_fma_f32 v192, v13, v192, 1.0
	v_mul_f32_e32 v181, v213, v192
	v_add_f32_e32 v192, -1.0, v190
	v_fma_f32 v192, v14, v192, 1.0
	v_mul_f32_e32 v182, v214, v192
	v_add_f32_e32 v192, -1.0, v191
	v_fma_f32 v192, v15, v192, 1.0
	v_mul_f32_e32 v183, v215, v192
	v_max_f32_e32 v200, v200, v200
	v_max_f32_e32 v200, 0x179abe15, v200
	v_rsq_f32_e32 v201, v200
	v_mul_f32_e32 v192, v136, v176
	v_mul_f32_e32 v202, v16, v192
	v_mul_f32_e32 v160, v160, v201
	v_mul_f32_e32 v161, v161, v201
	v_mul_f32_e32 v162, v162, v201
	v_mul_f32_e32 v163, v163, v201
	v_mul_f32_e32 v164, v164, v201
	v_mul_f32_e32 v165, v165, v201
	v_mul_f32_e32 v166, v166, v201
	v_mul_f32_e32 v167, v167, v201
	v_mul_f32_e32 v168, v184, v160
	v_mul_f32_e32 v169, v185, v161
	v_mul_f32_e32 v170, v186, v162
	v_mul_f32_e32 v171, v187, v163
	v_mul_f32_e32 v172, v188, v164
	v_mul_f32_e32 v173, v189, v165
	v_mul_f32_e32 v174, v190, v166
	v_mul_f32_e32 v175, v191, v167
	ds_write_b128 v54, v[160:163] offset:20480
	ds_write_b128 v54, v[164:167] offset:20496
	ds_write_b128 v54, v[168:171] offset:20736
	ds_write_b128 v54, v[172:175] offset:20752
	ds_write_b128 v54, v[176:179] offset:20992
	ds_write_b128 v54, v[180:183] offset:21008
	ds_write_b128 v54, v[136:139] offset:21248
	ds_write_b128 v54, v[140:143] offset:21264
	ds_write_b128 v54, v[152:155] offset:21504
	ds_write_b128 v54, v[156:159] offset:21520
	v_mul_f32_e32 v192, v137, v177
	v_fmac_f32_e32 v202, v17, v192
	v_mul_f32_e32 v192, v138, v178
	v_fmac_f32_e32 v202, v18, v192
	v_mul_f32_e32 v192, v139, v179
	v_fmac_f32_e32 v202, v19, v192
	v_mul_f32_e32 v192, v140, v180
	v_fmac_f32_e32 v202, v20, v192
	v_mul_f32_e32 v192, v141, v181
	v_fmac_f32_e32 v202, v21, v192
	v_mul_f32_e32 v192, v142, v182
	v_fmac_f32_e32 v202, v22, v192
	v_mul_f32_e32 v192, v143, v183
	v_fmac_f32_e32 v202, v23, v192
	s_nop 1
	v_add_f32_dpp v202, v202, v202 quad_perm:[1,0,3,2] row_mask:0xf bank_mask:0xf bound_ctrl:1
	s_nop 1
	v_add_f32_dpp v202, v202, v202 quad_perm:[2,3,0,1] row_mask:0xf bank_mask:0xf bound_ctrl:1
	s_nop 1
	v_add_f32_dpp v202, v202, v202 row_half_mirror row_mask:0xf bank_mask:0xf bound_ctrl:1
	v_add_u32_e32 v205, s90, v56
	v_lshl_add_u32 v205, v205, 7, s64
	s_and_saveexec_b64 s[56:57], s[8:9]
	global_store_dword v205, v202, s[24:25]
	s_or_b64 exec, exec, s[56:57]
	v_mov_b32_e32 v56, v57
	s_waitcnt lgkmcnt(0)
	s_barrier
	s_add_i32 s10, s10, 1
	s_cmp_lt_u32 s10, 129
	s_cbranch_scc1 .Lmy_ks_loop
	s_waitcnt lgkmcnt(0)
	s_barrier

.LBB0_1162:
	s_add_i32 s93, s10, -2
	s_cmpk_lt_u32 s93, 0x80
	s_cselect_b64 s[8:9], -1, 0
	s_cmpk_gt_u32 s93, 0x7f
	s_branch .LBB0_1164
	s_add_i32 s94, s91, 16
	s_add_i32 s95, s92, -16
	s_and_b64 s[6:7], s[0:1], exec
	s_cselect_b32 s6, s94, s95
	s_or_b32 s6, s6, s90
	s_mulk_i32 s6, 0xe00
	v_add_lshl_u32 v0, s6, v126, 1
	s_waitcnt vmcnt(22)
	v_lshl_add_u64 v[138:139], s[72:73], 0, v[0:1]
	s_waitcnt vmcnt(19)
	v_add_co_u32_e32 v142, vcc, 0xffffe000, v138
	s_add_i32 s94, s91, 17
	s_waitcnt vmcnt(18)
	v_addc_co_u32_e32 v143, vcc, -1, v139, vcc
	s_sub_i32 s95, s92, 17
	s_waitcnt vmcnt(17)
	v_add_co_u32_e32 v144, vcc, 0xfffff000, v138
	s_and_b64 s[6:7], s[0:1], exec
	s_waitcnt vmcnt(16)
	v_addc_co_u32_e32 v145, vcc, -1, v139, vcc
	s_cselect_b32 s6, s94, s95
	s_waitcnt vmcnt(14)
	v_add_co_u32_e32 v148, vcc, s67, v138
	s_or_b32 s6, s6, s90
	s_waitcnt vmcnt(13)
	v_addc_co_u32_e32 v149, vcc, 0, v139, vcc
	s_mulk_i32 s6, 0xe00
	global_load_ushort v132, v0, s[72:73] offset:-2048
	global_load_ushort v133, v0, s[72:73]
	global_load_ushort v134, v0, s[72:73] offset:2048
	s_waitcnt vmcnt(14)
	v_add_co_u32_e32 v162, vcc, s77, v138
	v_add_lshl_u32 v0, s6, v126, 1
	s_waitcnt vmcnt(13)
	v_addc_co_u32_e32 v163, vcc, 0, v139, vcc
	s_waitcnt vmcnt(11)
	v_lshl_add_u64 v[164:165], s[72:73], 0, v[0:1]
	s_waitcnt vmcnt(10)
	v_add_co_u32_e32 v166, vcc, s81, v164
	s_add_i32 s94, s91, 18
	s_waitcnt vmcnt(9)
	v_addc_co_u32_e32 v167, vcc, -1, v165, vcc
	s_sub_i32 s95, s92, 18
	s_waitcnt vmcnt(7)
	v_add_co_u32_e32 v168, vcc, s85, v164
	s_and_b64 s[6:7], s[0:1], exec
	s_waitcnt vmcnt(6)
	v_addc_co_u32_e32 v169, vcc, -1, v165, vcc
	s_cselect_b32 s6, s94, s95
	global_load_ushort v138, v0, s[72:73] offset:-2048
	global_load_ushort v139, v0, s[72:73]
	global_load_ushort v141, v0, s[72:73] offset:2048
	global_load_ushort v140, v[142:143], off offset:-1024
	s_nop 0
	global_load_ushort v142, v[144:145], off offset:-3072
	global_load_ushort v143, v[144:145], off offset:-1024
	s_nop 0
	global_load_ushort v144, v[148:149], off offset:1024
	global_load_ushort v145, v[148:149], off offset:3072
	global_load_ushort v147, v[162:163], off offset:1024
	s_nop 0
	global_load_ushort v148, v[166:167], off offset:-1024
	global_load_ushort v149, v[168:169], off offset:-3072
	v_add_co_u32_e32 v166, vcc, s67, v164
	s_or_b32 s6, s6, s90
	s_nop 0
	v_addc_co_u32_e32 v167, vcc, 0, v165, vcc
	s_mulk_i32 s6, 0xe00
	v_add_co_u32_e32 v164, vcc, s77, v164
	v_add_lshl_u32 v0, s6, v126, 1
	s_nop 0
	v_addc_co_u32_e32 v165, vcc, 0, v165, vcc
	v_lshl_add_u64 v[190:191], s[72:73], 0, v[0:1]
	v_add_co_u32_e32 v170, vcc, s81, v190
	s_waitcnt vmcnt(16)
	s_nop 0
	v_addc_co_u32_e32 v171, vcc, -1, v191, vcc
	v_add_co_u32_e32 v192, vcc, s85, v190
	s_nop 1
	v_addc_co_u32_e32 v193, vcc, -1, v191, vcc
	v_add_co_u32_e32 v194, vcc, s67, v190
	s_nop 1
	v_addc_co_u32_e32 v195, vcc, 0, v191, vcc
	global_load_ushort v161, v[168:169], off offset:-1024
	global_load_ushort v162, v[166:167], off offset:1024
	global_load_ushort v163, v[166:167], off offset:3072
	s_nop 0
	global_load_ushort v164, v[164:165], off offset:1024
	s_nop 0
	global_load_ushort v165, v[170:171], off offset:-1024
	global_load_ushort v166, v[192:193], off offset:-3072
	global_load_ushort v167, v[192:193], off offset:-1024
	s_nop 0
	global_load_ushort v170, v[194:195], off offset:1024
	v_add_co_u32_e32 v190, vcc, s77, v190
	s_nop 1
	v_addc_co_u32_e32 v191, vcc, 0, v191, vcc
	global_load_ushort v168, v0, s[72:73] offset:-2048
	global_load_ushort v169, v0, s[72:73]
	global_load_ushort v171, v0, s[72:73] offset:2048
	global_load_ushort v172, v[194:195], off offset:3072
	global_load_ushort v175, v[190:191], off offset:1024

.LBB0_1166:
	s_add_i32 s8, s10, -4
	s_cmp_lt_i32 s8, 0
	s_branch .LBB0_1174
	s_and_b64 s[8:9], s[0:1], exec
	s_cselect_b32 s94, s91, s92
	s_cmpk_lt_u32 s94, 0x7ff
	s_cselect_b64 s[8:9], -1, 0
	v_cndmask_b32_e64 v0, 0, 1.0, s[8:9]
	s_waitcnt vmcnt(20)
	v_lshlrev_b32_e32 v191, 16, v152
	s_waitcnt vmcnt(17)
	v_lshlrev_b32_e32 v192, 16, v156
	v_lshlrev_b32_e32 v190, 16, v135
	v_fmac_f32_e32 v191, v0, v192
	v_fma_f32 v191, v191, 0.5, -v190
	v_lshlrev_b32_e32 v192, 16, v154
	s_waitcnt vmcnt(16)
	v_lshlrev_b32_e32 v193, 16, v157
	s_waitcnt vmcnt(8)
	v_fmac_f32_e32 v190, v123, v191
	v_lshlrev_b32_e32 v191, 16, v136
	v_fmac_f32_e32 v192, v0, v193
	v_fma_f32 v192, v192, 0.5, -v191
	v_lshlrev_b32_e32 v193, 16, v155
	v_lshlrev_b32_e32 v194, 16, v158
	s_waitcnt vmcnt(7)
	v_fmac_f32_e32 v191, v124, v192
	v_lshlrev_b32_e32 v192, 16, v137
	v_fmac_f32_e32 v193, v0, v194
	v_fma_f32 v0, v193, 0.5, -v192
	v_mul_f32_e32 v193, v120, v191
	v_mul_f32_e32 v194, v193, v193
	v_mov_b32_e32 v195, 0
	s_waitcnt vmcnt(6)
	v_fmac_f32_e32 v192, v125, v0
	v_mov_b32_dpp v194, v194 quad_perm:[1,0,3,2] row_mask:0xf bank_mask:0xf bound_ctrl:1
	v_fmac_f32_e32 v194, v193, v193
	ds_read_b32 v0, v127 offset:16640
	s_nop 0
	v_add_f32_dpp v194, v194, v194 quad_perm:[2,3,0,1] row_mask:0xf bank_mask:0xf bound_ctrl:1
	s_nop 1
	v_add_f32_dpp v194, v194, v194 row_half_mirror row_mask:0xf bank_mask:0xf bound_ctrl:1
	s_nop 1
	v_add_f32_dpp v194, v194, v194 row_mirror row_mask:0xf bank_mask:0xf bound_ctrl:1
	s_nop 1
	v_mov_b32_dpp v195, v194 row_bcast:15 row_mask:0xa bank_mask:0xf
	v_add_f32_e32 v194, v194, v195
	v_mov_b32_e32 v195, 0
	s_nop 1
	v_mov_b32_dpp v195, v194 row_bcast:31 row_mask:0xc bank_mask:0xf
	v_add_f32_e32 v194, v194, v195
	s_waitcnt lgkmcnt(0)
	v_add_f32_e32 v195, -1.0, v0
	v_readlane_b32 s8, v194, 63
	v_fma_f32 v195, v121, v195, 1.0
	v_mul_f32_e32 v191, v191, v195
	v_max_f32_e64 v194, s8, s8
	v_max_f32_e32 v194, 0x179abe15, v194
	v_rsq_f32_e32 v194, v194
	s_nop 0
	v_mul_f32_e32 v193, v193, v194
	v_mul_f32_e32 v0, v0, v193
	ds_write2st64_b32 v127, v193, v0 offset0:165 offset1:166
	ds_write2st64_b32 v127, v191, v190 offset0:167 offset1:168
	ds_write_b32 v127, v192 offset:43264
	v_mul_f32_e32 v0, v190, v191
	v_mul_f32_e32 v190, v122, v0
	s_nop 1
	v_mov_b32_dpp v190, v190 quad_perm:[1,0,3,2] row_mask:0xf bank_mask:0xf bound_ctrl:1
	v_fmac_f32_e32 v190, v122, v0
	s_nop 1
	v_add_f32_dpp v0, v190, v190 quad_perm:[2,3,0,1] row_mask:0xf bank_mask:0xf bound_ctrl:1
	v_mov_b32_e32 v190, 0
	s_nop 0
	v_add_f32_dpp v0, v0, v0 row_half_mirror row_mask:0xf bank_mask:0xf bound_ctrl:1
	s_nop 1
	v_add_f32_dpp v0, v0, v0 row_mirror row_mask:0xf bank_mask:0xf bound_ctrl:1
	s_nop 1
	v_mov_b32_dpp v190, v0 row_bcast:15 row_mask:0xa bank_mask:0xf
	v_add_f32_e32 v0, v0, v190
	v_mov_b32_e32 v190, 0
	s_nop 1
	v_mov_b32_dpp v190, v0 row_bcast:31 row_mask:0xc bank_mask:0xf
	v_add_f32_e32 v0, v0, v190
	s_nop 0
	v_readlane_b32 s95, v0, 63
	s_and_saveexec_b64 s[8:9], s[4:5]
	s_cbranch_execz .LBB0_1169
	s_add_i32 s94, s94, s90
	s_lshl_b32 s94, s94, 7
	s_or_b32 s94, s94, s64
	v_mov_b32_e32 v0, s94
	v_mov_b32_e32 v190, s95
	global_store_dword v0, v190, s[24:25]

.LBB0_1176:
	v_cndmask_b32_e64 v0, 0, 1, s[58:59]
	v_cmp_ne_u32_e64 s[8:9], 1, v0
	s_andn2_b64 vcc, exec, s[58:59]
	s_branch .LBB0_1178
	s_add_i32 s94, s91, 32
	s_sub_i32 s95, s92, 32
	s_and_b64 s[58:59], s[0:1], exec
	s_cselect_b32 s58, s94, s95
	s_or_b32 s58, s58, s90
	s_mulk_i32 s58, 0xe00
	v_add_lshl_u32 v0, s58, v126, 1
	s_waitcnt vmcnt(22)
	v_lshl_add_u64 v[150:151], s[72:73], 0, v[0:1]
	s_waitcnt vmcnt(19)
	v_add_co_u32_e32 v154, vcc, 0xffffe000, v150
	s_add_i32 s94, s91, 33
	s_waitcnt vmcnt(18)
	v_addc_co_u32_e32 v155, vcc, -1, v151, vcc
	s_sub_i32 s95, s92, 33
	s_waitcnt vmcnt(17)
	v_add_co_u32_e32 v156, vcc, 0xfffff000, v150
	s_and_b64 s[58:59], s[0:1], exec
	s_waitcnt vmcnt(16)
	v_addc_co_u32_e32 v157, vcc, -1, v151, vcc
	s_cselect_b32 s58, s94, s95
	s_waitcnt vmcnt(15)
	v_add_co_u32_e32 v158, vcc, s67, v150
	s_or_b32 s58, s58, s90
	s_waitcnt vmcnt(14)
	v_addc_co_u32_e32 v159, vcc, 0, v151, vcc
	s_mulk_i32 s58, 0xe00
	global_load_ushort v135, v0, s[72:73] offset:-2048
	global_load_ushort v136, v0, s[72:73]
	global_load_ushort v137, v0, s[72:73] offset:2048
	s_waitcnt vmcnt(13)
	v_add_co_u32_e32 v176, vcc, s77, v150
	v_add_lshl_u32 v0, s58, v126, 1
	s_waitcnt vmcnt(12)
	v_addc_co_u32_e32 v177, vcc, 0, v151, vcc
	s_waitcnt vmcnt(10)
	v_lshl_add_u64 v[178:179], s[72:73], 0, v[0:1]
	s_waitcnt vmcnt(9)
	v_add_co_u32_e32 v180, vcc, s81, v178
	s_add_i32 s94, s91, 34
	s_waitcnt vmcnt(7)
	v_addc_co_u32_e32 v181, vcc, -1, v179, vcc
	s_sub_i32 s95, s92, 34
	s_waitcnt vmcnt(6)
	v_add_co_u32_e32 v182, vcc, s85, v178
	s_and_b64 s[58:59], s[0:1], exec
	s_nop 0
	v_addc_co_u32_e32 v183, vcc, -1, v179, vcc
	s_cselect_b32 s58, s94, s95
	global_load_ushort v150, v0, s[72:73] offset:-2048
	global_load_ushort v151, v0, s[72:73]
	global_load_ushort v153, v0, s[72:73] offset:2048
	global_load_ushort v152, v[154:155], off offset:-1024
	s_nop 0
	global_load_ushort v154, v[156:157], off offset:-3072
	global_load_ushort v155, v[156:157], off offset:-1024
	s_nop 0
	global_load_ushort v156, v[158:159], off offset:1024
	global_load_ushort v157, v[158:159], off offset:3072
	s_nop 0
	global_load_ushort v158, v[176:177], off offset:1024
	global_load_ushort v159, v[180:181], off offset:-1024
	global_load_ushort v160, v[182:183], off offset:-3072
	v_add_co_u32_e32 v176, vcc, s67, v178
	s_or_b32 s58, s58, s90
	s_nop 0
	v_addc_co_u32_e32 v177, vcc, 0, v179, vcc
	s_mulk_i32 s58, 0xe00
	v_add_co_u32_e32 v178, vcc, s77, v178
	v_add_lshl_u32 v0, s58, v126, 1
	s_nop 0
	v_addc_co_u32_e32 v179, vcc, 0, v179, vcc
	s_waitcnt vmcnt(15)
	v_lshl_add_u64 v[184:185], s[72:73], 0, v[0:1]
	v_add_co_u32_e32 v180, vcc, s81, v184
	s_nop 1
	v_addc_co_u32_e32 v181, vcc, -1, v185, vcc
	v_add_co_u32_e32 v190, vcc, s85, v184
	s_nop 1
	v_addc_co_u32_e32 v191, vcc, -1, v185, vcc
	v_add_co_u32_e32 v192, vcc, s67, v184
	s_nop 1
	v_addc_co_u32_e32 v193, vcc, 0, v185, vcc
	global_load_ushort v173, v[182:183], off offset:-1024
	global_load_ushort v174, v[176:177], off offset:1024
	s_nop 0
	global_load_ushort v176, v[176:177], off offset:3072
	s_nop 0
	global_load_ushort v177, v[178:179], off offset:1024
	s_nop 0
	global_load_ushort v178, v[180:181], off offset:-1024
	global_load_ushort v179, v[190:191], off offset:-3072
	s_nop 0
	global_load_ushort v180, v[190:191], off offset:-1024
	global_load_ushort v183, v[192:193], off offset:1024
	v_add_co_u32_e32 v190, vcc, s77, v184
	s_nop 1
	v_addc_co_u32_e32 v191, vcc, 0, v185, vcc
	global_load_ushort v181, v0, s[72:73] offset:-2048
	global_load_ushort v182, v0, s[72:73]
	global_load_ushort v184, v0, s[72:73] offset:2048
	global_load_ushort v185, v[192:193], off offset:3072
	global_load_ushort v186, v[190:191], off offset:1024

.LBB0_1180:
	s_and_b64 vcc, exec, s[6:7]
	s_branch .LBB0_1158
	s_waitcnt vmcnt(20)
	v_lshlrev_b32_e32 v98, 16, v140
	s_waitcnt vmcnt(17)
	v_lshlrev_b32_e32 v99, 16, v144
	v_lshlrev_b32_e32 v0, 16, v132
	v_add_f32_e32 v98, v98, v99
	v_fma_f32 v98, v98, 0.5, -v0
	v_lshlrev_b32_e32 v99, 16, v142
	s_waitcnt vmcnt(16)
	v_lshlrev_b32_e32 v100, 16, v145
	s_waitcnt vmcnt(8)
	v_fmac_f32_e32 v0, v123, v98
	v_lshlrev_b32_e32 v98, 16, v133
	v_add_f32_e32 v99, v99, v100
	v_fma_f32 v99, v99, 0.5, -v98
	s_waitcnt vmcnt(7)
	v_fmac_f32_e32 v98, v124, v99
	v_lshlrev_b32_e32 v100, 16, v143
	v_lshlrev_b32_e32 v101, 16, v147
	v_add_f32_e32 v100, v100, v101
	v_mul_f32_e32 v101, v120, v98
	v_mul_f32_e32 v102, v101, v101
	v_mov_b32_e32 v103, 0
	v_lshlrev_b32_e32 v99, 16, v134
	v_mov_b32_dpp v102, v102 quad_perm:[1,0,3,2] row_mask:0xf bank_mask:0xf bound_ctrl:1
	v_fmac_f32_e32 v102, v101, v101
	v_fma_f32 v100, v100, 0.5, -v99
	s_waitcnt vmcnt(6)
	v_fmac_f32_e32 v99, v125, v100
	v_add_f32_dpp v102, v102, v102 quad_perm:[2,3,0,1] row_mask:0xf bank_mask:0xf bound_ctrl:1
	ds_read_b32 v100, v127 offset:12544
	s_nop 0
	v_add_f32_dpp v102, v102, v102 row_half_mirror row_mask:0xf bank_mask:0xf bound_ctrl:1
	s_nop 1
	v_add_f32_dpp v102, v102, v102 row_mirror row_mask:0xf bank_mask:0xf bound_ctrl:1
	s_nop 1
	v_mov_b32_dpp v103, v102 row_bcast:15 row_mask:0xa bank_mask:0xf
	v_add_f32_e32 v102, v102, v103
	v_mov_b32_e32 v103, 0
	s_nop 1
	v_mov_b32_dpp v103, v102 row_bcast:31 row_mask:0xc bank_mask:0xf
	v_add_f32_e32 v102, v102, v103
	s_waitcnt lgkmcnt(0)
	v_add_f32_e32 v103, -1.0, v100
	v_readlane_b32 s6, v102, 63
	v_fma_f32 v103, v121, v103, 1.0
	v_mul_f32_e32 v98, v98, v103
	v_max_f32_e64 v102, s6, s6
	v_max_f32_e32 v102, 0x179abe15, v102
	v_rsq_f32_e32 v102, v102
	s_nop 0
	v_mul_f32_e32 v101, v101, v102
	v_mul_f32_e32 v100, v100, v101
	ds_write2st64_b32 v127, v101, v100 offset0:85 offset1:86
	ds_write2st64_b32 v127, v98, v0 offset0:87 offset1:88
	ds_write_b32 v127, v99 offset:22784
	v_mul_f32_e32 v0, v0, v98
	v_mul_f32_e32 v98, v122, v0
	s_nop 1
	v_mov_b32_dpp v98, v98 quad_perm:[1,0,3,2] row_mask:0xf bank_mask:0xf bound_ctrl:1
	v_fmac_f32_e32 v98, v122, v0
	s_nop 1
	v_add_f32_dpp v0, v98, v98 quad_perm:[2,3,0,1] row_mask:0xf bank_mask:0xf bound_ctrl:1
	v_mov_b32_e32 v98, 0
	s_nop 0
	v_add_f32_dpp v0, v0, v0 row_half_mirror row_mask:0xf bank_mask:0xf bound_ctrl:1
	s_nop 1
	v_add_f32_dpp v0, v0, v0 row_mirror row_mask:0xf bank_mask:0xf bound_ctrl:1
	s_nop 1
	v_mov_b32_dpp v98, v0 row_bcast:15 row_mask:0xa bank_mask:0xf
	v_add_f32_e32 v0, v0, v98
	v_mov_b32_e32 v98, 0
	s_nop 1
	v_mov_b32_dpp v98, v0 row_bcast:31 row_mask:0xc bank_mask:0xf
	v_add_f32_e32 v0, v0, v98
	s_nop 0
	v_readlane_b32 s8, v0, 63
	s_and_saveexec_b64 s[6:7], s[4:5]
	s_cbranch_execz .LBB0_1183
	s_add_i32 s9, s91, 16
	s_add_i32 s94, s92, -16
	s_and_b64 s[58:59], s[0:1], exec
	s_cselect_b32 s9, s9, s94
	s_or_b32 s9, s9, s90
	s_lshl_b32 s9, s9, 7
	s_or_b32 s9, s9, s64
	v_mov_b32_e32 v0, s9
	v_mov_b32_e32 v98, s8
	global_store_dword v0, v98, s[24:25]

.LBB0_1195:
	s_add_i32 s93, s58, -2
	s_cmpk_lt_u32 s93, 0x80
	s_cselect_b64 s[8:9], -1, 0
	s_cmpk_gt_u32 s93, 0x7f
	s_branch .LBB0_1197
	s_add_i32 s10, s91, 16
	s_add_i32 s94, s92, -16
	s_and_b64 s[6:7], s[0:1], exec
	s_cselect_b32 s6, s10, s94
	s_or_b32 s7, s6, s90
	s_mulk_i32 s7, 0xe00
	s_cmp_eq_u32 s6, 0
	v_add_lshl_u32 v0, s7, v142, 1
	s_cselect_b32 s7, 0, 0xffffe400
	s_cmpk_lt_u32 s6, 0x7ff
	v_add_u32_e32 v4, s7, v0
	v_lshl_add_u64 v[2:3], s[72:73], 0, v[0:1]
	s_cselect_b32 s10, 0x1c00, 0
	v_lshl_add_u64 v[2:3], v[2:3], 0, s[10:11]
	global_load_ushort v5, v0, s[72:73] offset:-2048
	global_load_ushort v102, v0, s[72:73]
	s_nop 0
	global_load_ushort v0, v0, s[72:73] offset:2048
	s_nop 0
	global_load_ushort v103, v4, s[72:73] offset:-2048
	global_load_ushort v104, v4, s[72:73]
	s_nop 0
	global_load_ushort v4, v4, s[72:73] offset:2048
	s_nop 0
	global_load_ushort v105, v[2:3], off offset:-2048
	global_load_ushort v150, v[2:3], off
	global_load_ushort v151, v[2:3], off offset:2048
	s_waitcnt vmcnt(7)
	v_perm_b32 v2, v102, v5, s86
	s_waitcnt vmcnt(5)
	v_perm_b32 v3, v103, v0, s86
	s_waitcnt vmcnt(3)
	v_perm_b32 v4, v4, v104, s86
	s_waitcnt vmcnt(1)
	v_perm_b32 v5, v150, v105, s86
	s_waitcnt vmcnt(0)
	v_bfi_b32 v6, s87, v151, v6

.LBB0_1199:
	s_add_i32 s8, s58, -4
	s_cmp_lt_i32 s8, 0
	s_branch .LBB0_1203
	s_and_b64 s[8:9], s[0:1], exec
	s_cselect_b32 s10, s91, s92
	s_cmpk_lt_u32 s10, 0x7ff
	s_cselect_b64 s[8:9], -1, 0
	v_cndmask_b32_e64 v0, 0, 1.0, s[8:9]
	v_lshlrev_b32_e32 v103, 16, v8
	v_and_b32_e32 v104, 0xffff0000, v9
	v_and_b32_e32 v102, 0xffff0000, v6
	v_fmac_f32_e32 v103, v0, v104
	v_fma_f32 v103, v103, 0.5, -v102
	v_and_b32_e32 v104, 0xffff0000, v8
	v_lshlrev_b32_e32 v105, 16, v10
	s_waitcnt vmcnt(8)
	v_fmac_f32_e32 v102, v139, v103
	v_lshlrev_b32_e32 v103, 16, v7
	v_fmac_f32_e32 v104, v0, v105
	v_fma_f32 v104, v104, 0.5, -v103
	v_lshlrev_b32_e32 v105, 16, v9
	v_and_b32_e32 v150, 0xffff0000, v10
	s_waitcnt vmcnt(7)
	v_fmac_f32_e32 v103, v140, v104
	v_and_b32_e32 v104, 0xffff0000, v7
	v_fmac_f32_e32 v105, v0, v150
	v_fma_f32 v0, v105, 0.5, -v104
	s_waitcnt vmcnt(6)
	v_fmac_f32_e32 v104, v141, v0
	v_mul_f32_e32 v0, v136, v103
	v_mul_f32_e32 v105, v0, v0
	v_mov_b32_e32 v151, 0
	ds_read_b32 v150, v145 offset:16384
	v_mov_b32_dpp v105, v105 quad_perm:[1,0,3,2] row_mask:0xf bank_mask:0xf bound_ctrl:1
	v_fmac_f32_e32 v105, v0, v0
	s_nop 1
	v_add_f32_dpp v105, v105, v105 quad_perm:[2,3,0,1] row_mask:0xf bank_mask:0xf bound_ctrl:1
	s_nop 1
	v_add_f32_dpp v105, v105, v105 row_half_mirror row_mask:0xf bank_mask:0xf bound_ctrl:1
	s_nop 1
	v_add_f32_dpp v105, v105, v105 row_mirror row_mask:0xf bank_mask:0xf bound_ctrl:1
	s_nop 1
	v_mov_b32_dpp v151, v105 row_bcast:15 row_mask:0xa bank_mask:0xf
	v_add_f32_e32 v105, v105, v151
	v_mov_b32_e32 v151, 0
	s_nop 1
	v_mov_b32_dpp v151, v105 row_bcast:31 row_mask:0xc bank_mask:0xf
	v_add_f32_e32 v105, v105, v151
	s_waitcnt lgkmcnt(0)
	v_add_f32_e32 v151, -1.0, v150
	v_readlane_b32 s8, v105, 63
	v_fma_f32 v151, v137, v151, 1.0
	v_mul_f32_e32 v103, v103, v151
	v_max_f32_e64 v105, s8, s8
	v_max_f32_e32 v105, 0x179abe15, v105
	v_rsq_f32_e32 v105, v105
	s_nop 0
	v_mul_f32_e32 v0, v0, v105
	v_mul_f32_e32 v105, v150, v0
	ds_write2st64_b32 v145, v0, v105 offset0:160 offset1:161
	ds_write2st64_b32 v145, v103, v102 offset0:162 offset1:163
	ds_write_b32 v145, v104 offset:41984
	v_mul_f32_e32 v0, v102, v103
	v_mul_f32_e32 v102, v138, v0
	s_nop 1
	v_mov_b32_dpp v102, v102 quad_perm:[1,0,3,2] row_mask:0xf bank_mask:0xf bound_ctrl:1
	v_fmac_f32_e32 v102, v138, v0
	s_nop 1
	v_add_f32_dpp v0, v102, v102 quad_perm:[2,3,0,1] row_mask:0xf bank_mask:0xf bound_ctrl:1
	v_mov_b32_e32 v102, 0
	s_nop 0
	v_add_f32_dpp v0, v0, v0 row_half_mirror row_mask:0xf bank_mask:0xf bound_ctrl:1
	s_nop 1
	v_add_f32_dpp v0, v0, v0 row_mirror row_mask:0xf bank_mask:0xf bound_ctrl:1
	s_nop 1
	v_mov_b32_dpp v102, v0 row_bcast:15 row_mask:0xa bank_mask:0xf
	v_add_f32_e32 v0, v0, v102
	v_mov_b32_e32 v102, 0
	s_nop 1
	v_mov_b32_dpp v102, v0 row_bcast:31 row_mask:0xc bank_mask:0xf
	v_add_f32_e32 v0, v0, v102
	s_nop 0
	v_readlane_b32 s94, v0, 63
	s_and_saveexec_b64 s[8:9], s[4:5]
	s_cbranch_execz .LBB0_1202
	s_add_i32 s10, s10, s90
	s_lshl_b32 s10, s10, 7
	s_or_b32 s10, s10, s64
	v_mov_b32_e32 v0, s10
	v_mov_b32_e32 v102, s94
	global_store_dword v0, v102, s[24:25]

.LBB0_1205:
	v_cndmask_b32_e64 v0, 0, 1, s[56:57]
	v_cmp_ne_u32_e64 s[8:9], 1, v0
	s_andn2_b64 vcc, exec, s[56:57]
	s_branch .LBB0_1207
	s_add_i32 s10, s91, 32
	s_sub_i32 s94, s92, 32
	s_and_b64 s[56:57], s[0:1], exec
	s_cselect_b32 s10, s10, s94
	s_or_b32 s10, s10, s90
	s_mulk_i32 s10, 0xe00
	v_add_lshl_u32 v0, s10, v142, 1
	v_lshl_add_u64 v[8:9], s[72:73], 0, v[0:1]
	v_add_co_u32_e32 v102, vcc, 0xffffe000, v8
	s_nop 1
	v_addc_co_u32_e32 v103, vcc, -1, v9, vcc
	v_add_co_u32_e32 v104, vcc, 0xfffff000, v8
	s_nop 1
	v_addc_co_u32_e32 v105, vcc, -1, v9, vcc
	v_add_co_u32_e32 v150, vcc, s67, v8
	s_nop 1
	v_addc_co_u32_e32 v151, vcc, 0, v9, vcc
	v_add_co_u32_e32 v8, vcc, s77, v8
	s_nop 1
	v_addc_co_u32_e32 v9, vcc, 0, v9, vcc
	global_load_ushort v10, v[8:9], off offset:1024
	global_load_ushort v7, v0, s[72:73]
	s_nop 0
	global_load_ushort v8, v0, s[72:73] offset:2048
	global_load_ushort v9, v[102:103], off offset:-1024
	s_nop 0
	global_load_ushort v102, v[104:105], off offset:-3072
	global_load_ushort v103, v[104:105], off offset:-1024
	s_nop 0
	global_load_ushort v104, v[150:151], off offset:1024
	global_load_ushort v105, v[150:151], off offset:3072
	s_nop 0
	global_load_ushort v0, v0, s[72:73] offset:-2048
	s_waitcnt vmcnt(6)
	v_perm_b32 v7, v8, v7, s86
	s_waitcnt vmcnt(4)
	v_perm_b32 v8, v102, v9, s86
	s_waitcnt vmcnt(2)
	v_perm_b32 v9, v104, v103, s86
	s_waitcnt vmcnt(1)
	v_perm_b32 v10, v10, v105, s86
	s_waitcnt vmcnt(0)
	v_perm_b32 v6, v0, v6, s86

.LBB0_1209:
	s_and_b64 vcc, exec, s[6:7]
	s_branch .LBB0_1191
	s_add_i32 s8, s91, 16
	s_add_i32 s9, s92, -16
	s_and_b64 s[6:7], s[0:1], exec
	s_cselect_b32 s8, s8, s9
	s_cmp_eq_u32 s8, 0
	s_cselect_b64 s[6:7], -1, 0
	s_cmpk_lt_u32 s8, 0x7ff
	v_cndmask_b32_e64 v0, 1.0, 0, s[6:7]
	s_cselect_b64 s[6:7], -1, 0
	v_cndmask_b32_e64 v11, 0, 1.0, s[6:7]
	v_lshlrev_b32_e32 v104, 16, v5
	v_and_b32_e32 v103, 0xffff0000, v3
	v_mul_f32_e32 v104, v11, v104
	v_lshlrev_b32_e32 v102, 16, v2
	v_fmac_f32_e32 v104, v0, v103
	v_and_b32_e32 v105, 0xffff0000, v5
	v_fma_f32 v103, v104, 0.5, -v102
	v_lshlrev_b32_e32 v104, 16, v4
	v_mul_f32_e32 v105, v11, v105
	s_waitcnt vmcnt(8)
	v_fmac_f32_e32 v102, v139, v103
	v_and_b32_e32 v103, 0xffff0000, v2
	v_fmac_f32_e32 v105, v0, v104
	v_lshlrev_b32_e32 v112, 16, v6
	v_fma_f32 v104, v105, 0.5, -v103
	v_and_b32_e32 v105, 0xffff0000, v4
	v_mul_f32_e32 v11, v11, v112
	s_waitcnt vmcnt(7)
	v_fmac_f32_e32 v103, v140, v104
	v_lshlrev_b32_e32 v104, 16, v3
	v_fmac_f32_e32 v11, v0, v105
	v_fma_f32 v0, v11, 0.5, -v104
	s_waitcnt vmcnt(6)
	v_fmac_f32_e32 v104, v141, v0
	v_mul_f32_e32 v0, v136, v103
	v_mul_f32_e32 v11, v0, v0
	v_mov_b32_e32 v112, 0
	ds_read_b32 v105, v145 offset:12288
	v_mov_b32_dpp v11, v11 quad_perm:[1,0,3,2] row_mask:0xf bank_mask:0xf bound_ctrl:1
	v_fmac_f32_e32 v11, v0, v0
	s_nop 1
	v_add_f32_dpp v11, v11, v11 quad_perm:[2,3,0,1] row_mask:0xf bank_mask:0xf bound_ctrl:1
	s_nop 1
	v_add_f32_dpp v11, v11, v11 row_half_mirror row_mask:0xf bank_mask:0xf bound_ctrl:1
	s_nop 1
	v_add_f32_dpp v11, v11, v11 row_mirror row_mask:0xf bank_mask:0xf bound_ctrl:1
	s_nop 1
	v_mov_b32_dpp v112, v11 row_bcast:15 row_mask:0xa bank_mask:0xf
	v_add_f32_e32 v11, v11, v112
	v_mov_b32_e32 v112, 0
	s_nop 1
	v_mov_b32_dpp v112, v11 row_bcast:31 row_mask:0xc bank_mask:0xf
	v_add_f32_e32 v11, v11, v112
	s_waitcnt lgkmcnt(0)
	v_add_f32_e32 v112, -1.0, v105
	v_readlane_b32 s6, v11, 63
	v_fma_f32 v112, v137, v112, 1.0
	v_mul_f32_e32 v103, v103, v112
	v_max_f32_e64 v11, s6, s6
	v_max_f32_e32 v11, 0x179abe15, v11
	v_rsq_f32_e32 v11, v11
	s_nop 0
	v_mul_f32_e32 v0, v0, v11
	v_mul_f32_e32 v11, v105, v0
	ds_write2st64_b32 v145, v0, v11 offset0:80 offset1:81
	ds_write2st64_b32 v145, v103, v102 offset0:82 offset1:83
	ds_write_b32 v145, v104 offset:21504
	v_mul_f32_e32 v0, v102, v103
	v_mul_f32_e32 v11, v138, v0
	s_nop 1
	v_mov_b32_dpp v11, v11 quad_perm:[1,0,3,2] row_mask:0xf bank_mask:0xf bound_ctrl:1
	v_fmac_f32_e32 v11, v138, v0
	s_nop 1
	v_add_f32_dpp v0, v11, v11 quad_perm:[2,3,0,1] row_mask:0xf bank_mask:0xf bound_ctrl:1
	v_mov_b32_e32 v11, 0
	s_nop 0
	v_add_f32_dpp v0, v0, v0 row_half_mirror row_mask:0xf bank_mask:0xf bound_ctrl:1
	s_nop 1
	v_add_f32_dpp v0, v0, v0 row_mirror row_mask:0xf bank_mask:0xf bound_ctrl:1
	s_nop 1
	v_mov_b32_dpp v11, v0 row_bcast:15 row_mask:0xa bank_mask:0xf
	v_add_f32_e32 v0, v0, v11
	v_mov_b32_e32 v11, 0
	s_nop 1
	v_mov_b32_dpp v11, v0 row_bcast:31 row_mask:0xc bank_mask:0xf
	v_add_f32_e32 v0, v0, v11
	s_nop 0
	v_readlane_b32 s9, v0, 63
	s_and_saveexec_b64 s[6:7], s[4:5]
	s_cbranch_execz .LBB0_1190
	s_or_b32 s8, s8, s90
	s_lshl_b32 s8, s8, 7
	s_or_b32 s8, s8, s64
	v_mov_b32_e32 v0, s8
	v_mov_b32_e32 v11, s9
	global_store_dword v0, v11, s[24:25]
	s_branch .LBB0_1190
